# staging waves: partial-sum reduction with packed adds
# baseline (speedup 1.0000x reference)
.Lsc_G_gom0:
	s_waitcnt vmcnt(10)
	v_lshlrev_b32_e32 v64, 16, v36
	v_and_b32_e32 v65, 0xffff0000, v36
	v_mul_f32_e32 v64, 0x3fb8aa3b, v64
	v_mul_f32_e32 v65, 0x3fb8aa3b, v65
	v_lshlrev_b32_e32 v66, 16, v37
	v_and_b32_e32 v67, 0xffff0000, v37
	v_mul_f32_e32 v66, 0x3fb8aa3b, v66
	v_mul_f32_e32 v67, 0x3fb8aa3b, v67
	v_lshlrev_b32_e32 v68, 16, v38
	v_and_b32_e32 v69, 0xffff0000, v38
	v_mul_f32_e32 v68, 0x3fb8aa3b, v68
	v_mul_f32_e32 v69, 0x3fb8aa3b, v69
	v_lshlrev_b32_e32 v70, 16, v39
	v_and_b32_e32 v71, 0xffff0000, v39
	v_mul_f32_e32 v70, 0x3fb8aa3b, v70
	v_mul_f32_e32 v71, 0x3fb8aa3b, v71
	ds_write_b128 v153, v[64:67]
	ds_write_b128 v153, v[68:71] offset:128
	s_waitcnt lgkmcnt(0)
	ds_read_b32 v124, v154 offset:0
	ds_read_b32 v125, v154 offset:256
	ds_read_b32 v126, v154 offset:512
	ds_read_b32 v127, v154 offset:768
	ds_read_b32 v128, v154 offset:1024
	ds_read_b32 v129, v154 offset:1280
	ds_read_b32 v130, v154 offset:1536
	ds_read_b32 v131, v154 offset:1792
	v_lshlrev_b32_e32 v108, 16, v32
	v_and_b32_e32 v109, 0xffff0000, v32
	v_lshlrev_b32_e32 v110, 16, v40
	v_and_b32_e32 v111, 0xffff0000, v40
	v_lshlrev_b32_e32 v96, 16, v28
	v_and_b32_e32 v97, 0xffff0000, v28
	v_pk_add_f32 v[112:113], v[110:111], -1.0 op_sel_hi:[1,0]
	v_pk_mul_f32 v[114:115], v[12:13], v[108:109]
	v_pk_fma_f32 v[112:113], v[20:21], v[112:113], 1.0 op_sel_hi:[1,1,0]
	v_pk_mul_f32 v[88:89], v[44:45], v[114:115] op_sel_hi:[0,1]
	v_pk_mul_f32 v[72:73], v[112:113], v[108:109]
	v_pk_mul_f32 v[80:81], v[88:89], v[110:111]
	v_lshlrev_b32_e32 v108, 16, v33
	v_and_b32_e32 v109, 0xffff0000, v33
	v_lshlrev_b32_e32 v110, 16, v41
	v_and_b32_e32 v111, 0xffff0000, v41
	v_lshlrev_b32_e32 v98, 16, v29
	v_and_b32_e32 v99, 0xffff0000, v29
	v_pk_add_f32 v[112:113], v[110:111], -1.0 op_sel_hi:[1,0]
	v_pk_mul_f32 v[114:115], v[14:15], v[108:109]
	v_pk_fma_f32 v[112:113], v[22:23], v[112:113], 1.0 op_sel_hi:[1,1,0]
	v_pk_mul_f32 v[90:91], v[44:45], v[114:115] op_sel_hi:[0,1]
	v_pk_mul_f32 v[74:75], v[112:113], v[108:109]
	v_pk_mul_f32 v[82:83], v[90:91], v[110:111]
	v_lshlrev_b32_e32 v108, 16, v34
	v_and_b32_e32 v109, 0xffff0000, v34
	v_lshlrev_b32_e32 v110, 16, v42
	v_and_b32_e32 v111, 0xffff0000, v42
	v_lshlrev_b32_e32 v100, 16, v30
	v_and_b32_e32 v101, 0xffff0000, v30
	v_pk_add_f32 v[112:113], v[110:111], -1.0 op_sel_hi:[1,0]
	v_pk_mul_f32 v[114:115], v[16:17], v[108:109]
	v_pk_fma_f32 v[112:113], v[24:25], v[112:113], 1.0 op_sel_hi:[1,1,0]
	v_pk_mul_f32 v[92:93], v[44:45], v[114:115] op_sel_hi:[0,1]
	v_pk_mul_f32 v[76:77], v[112:113], v[108:109]
	v_pk_mul_f32 v[84:85], v[92:93], v[110:111]
	v_lshlrev_b32_e32 v108, 16, v35
	v_and_b32_e32 v109, 0xffff0000, v35
	v_lshlrev_b32_e32 v110, 16, v43
	v_and_b32_e32 v111, 0xffff0000, v43
	v_lshlrev_b32_e32 v102, 16, v31
	v_and_b32_e32 v103, 0xffff0000, v31
	v_pk_add_f32 v[112:113], v[110:111], -1.0 op_sel_hi:[1,0]
	v_pk_mul_f32 v[114:115], v[18:19], v[108:109]
	v_pk_fma_f32 v[112:113], v[26:27], v[112:113], 1.0 op_sel_hi:[1,1,0]
	v_pk_mul_f32 v[94:95], v[44:45], v[114:115] op_sel_hi:[0,1]
	v_pk_mul_f32 v[78:79], v[112:113], v[108:109]
	v_pk_mul_f32 v[86:87], v[94:95], v[110:111]
	v_lshlrev_b32_e32 v104, 16, v45
	v_and_b32_e32 v105, 0xffff0000, v45
	s_waitcnt lgkmcnt(0)
	v_add_f32_e32 v125, v124, v125
	v_add_f32_e32 v126, v125, v126
	v_add_f32_e32 v127, v126, v127
	v_add_f32_e32 v128, v127, v128
	v_add_f32_e32 v129, v128, v129
	v_add_f32_e32 v130, v129, v130
	v_add_f32_e32 v131, v130, v131
	v_exp_f32_e64 v124, -v124
	v_exp_f32_e64 v125, -v125
	v_exp_f32_e64 v126, -v126
	v_exp_f32_e64 v127, -v127
	v_exp_f32_e64 v128, -v128
	v_exp_f32_e64 v129, -v129
	v_exp_f32_e64 v130, -v130
	v_exp_f32_e64 v131, -v131
	s_nop 0
	ds_write_b32 v155, v124 offset:256
	ds_write_b32 v155, v125 offset:512
	ds_write_b32 v155, v126 offset:768
	ds_write_b32 v155, v127 offset:1024
	ds_write_b32 v155, v128 offset:1280
	ds_write_b32 v155, v129 offset:1536
	ds_write_b32 v155, v130 offset:1792
	ds_write_b32 v155, v131 offset:2048
	ds_write_b32 v159, v131 offset:0
	s_waitcnt lgkmcnt(0)
	ds_read_b128 v[64:67], v153 offset:2048
	ds_read_b128 v[68:71], v153 offset:2176
	ds_read_b128 v[116:119], v153 offset:2304
	ds_read_b128 v[120:123], v153 offset:2432
	s_waitcnt lgkmcnt(0)
	v_rcp_f32_e32 v124, v116
	v_rcp_f32_e32 v125, v117
	v_rcp_f32_e32 v126, v118
	v_rcp_f32_e32 v127, v119
	v_rcp_f32_e32 v128, v120
	v_rcp_f32_e32 v129, v121
	v_rcp_f32_e32 v130, v122
	v_rcp_f32_e32 v131, v123
	s_nop 1
	v_pk_mul_f32 v[72:73], v[72:73], v[124:125]
	v_pk_mul_f32 v[80:81], v[80:81], v[124:125]
	v_pk_mul_f32 v[88:89], v[88:89], v[64:65]
	v_pk_mul_f32 v[96:97], v[96:97], v[116:117]
	v_pk_mul_f32 v[74:75], v[74:75], v[126:127]
	v_pk_mul_f32 v[82:83], v[82:83], v[126:127]
	v_pk_mul_f32 v[90:91], v[90:91], v[66:67]
	v_pk_mul_f32 v[98:99], v[98:99], v[118:119]
	v_pk_mul_f32 v[76:77], v[76:77], v[128:129]
	v_pk_mul_f32 v[84:85], v[84:85], v[128:129]
	v_pk_mul_f32 v[92:93], v[92:93], v[68:69]
	v_pk_mul_f32 v[100:101], v[100:101], v[120:121]
	v_pk_mul_f32 v[78:79], v[78:79], v[130:131]
	v_pk_mul_f32 v[86:87], v[86:87], v[130:131]
	v_pk_mul_f32 v[94:95], v[94:95], v[70:71]
	v_pk_mul_f32 v[102:103], v[102:103], v[122:123]
	ds_write_b128 v8, v[72:75] offset:0
	ds_write_b128 v8, v[76:79] offset:128
	ds_write_b128 v8, v[80:83] offset:256
	ds_write_b128 v8, v[84:87] offset:384
	ds_write2_b32 v138, v96, v97 offset0:1 offset1:3
	ds_write2_b32 v139, v88, v89 offset0:0 offset1:2
	ds_write2_b32 v138, v98, v99 offset0:65 offset1:67
	ds_write2_b32 v139, v90, v91 offset0:64 offset1:66
	ds_write2_b32 v138, v100, v101 offset0:33 offset1:35
	ds_write2_b32 v139, v92, v93 offset0:32 offset1:34
	ds_write2_b32 v138, v102, v103 offset0:97 offset1:99
	ds_write2_b32 v139, v94, v95 offset0:96 offset1:98
	ds_write2_b32 v142, v104, v105 offset1:36
	s_and_saveexec_b64 s[68:69], s[12:13]
	ds_write_b128 v158, v[88:91] offset:0
	ds_write_b128 v158, v[92:95] offset:128
	s_mov_b64 exec, s[68:69]
	global_load_dwordx2 v[28:29], v5, s[36:37]
	global_load_dwordx2 v[30:31], v5, s[36:37] offset:64
	global_load_dwordx2 v[32:33], v5, s[38:39]
	global_load_dwordx2 v[34:35], v5, s[38:39] offset:64
	global_load_dwordx2 v[36:37], v5, s[40:41]
	global_load_dwordx2 v[38:39], v5, s[40:41] offset:64
	global_load_dwordx2 v[40:41], v5, s[42:43]
	global_load_dwordx2 v[42:43], v5, s[42:43] offset:64
	global_load_dword v44, v6, s[46:47]
	global_load_dword v45, v9, s[44:45]
	v_add_u32_e32 v5, s54, v5
	v_add_u32_e32 v6, s55, v6
	v_add_u32_e32 v9, s54, v9
	ds_read_b128 v[120:123], v11 offset:0
	ds_read_b128 v[124:127], v11 offset:16
	ds_read_b128 v[128:131], v11 offset:32
	ds_read_b128 v[132:135], v11 offset:48
	s_waitcnt lgkmcnt(0)
	v_pk_add_f32 v[120:121], v[120:121], v[122:123]
	v_pk_add_f32 v[124:125], v[124:125], v[126:127]
	v_pk_add_f32 v[120:121], v[120:121], v[124:125]
	v_add_f32_e32 v136, v120, v121
	v_pk_add_f32 v[128:129], v[128:129], v[130:131]
	v_pk_add_f32 v[132:133], v[132:133], v[134:135]
	v_pk_add_f32 v[128:129], v[128:129], v[132:133]
	v_add_f32_e32 v137, v128, v129
	global_store_dwordx2 v7, v[136:137], s[48:49]
	v_add_u32_e32 v7, s64, v7
	s_add_i32 s6, s6, 1
	v_add_u32_e32 v146, 1, v146
	s_waitcnt lgkmcnt(0)
	ds_write_b32 v145, v146
	s_sub_u32 s65, s6, 1
	s_mov_b32 s69, 0x100000

.Lsc_G_gom1:
	s_waitcnt vmcnt(10)
	v_lshlrev_b32_e32 v64, 16, v54
	v_and_b32_e32 v65, 0xffff0000, v54
	v_mul_f32_e32 v64, 0x3fb8aa3b, v64
	v_mul_f32_e32 v65, 0x3fb8aa3b, v65
	v_lshlrev_b32_e32 v66, 16, v55
	v_and_b32_e32 v67, 0xffff0000, v55
	v_mul_f32_e32 v66, 0x3fb8aa3b, v66
	v_mul_f32_e32 v67, 0x3fb8aa3b, v67
	v_lshlrev_b32_e32 v68, 16, v56
	v_and_b32_e32 v69, 0xffff0000, v56
	v_mul_f32_e32 v68, 0x3fb8aa3b, v68
	v_mul_f32_e32 v69, 0x3fb8aa3b, v69
	v_lshlrev_b32_e32 v70, 16, v57
	v_and_b32_e32 v71, 0xffff0000, v57
	v_mul_f32_e32 v70, 0x3fb8aa3b, v70
	v_mul_f32_e32 v71, 0x3fb8aa3b, v71
	ds_write_b128 v153, v[64:67]
	ds_write_b128 v153, v[68:71] offset:128
	s_waitcnt lgkmcnt(0)
	ds_read_b32 v124, v154 offset:0
	ds_read_b32 v125, v154 offset:256
	ds_read_b32 v126, v154 offset:512
	ds_read_b32 v127, v154 offset:768
	ds_read_b32 v128, v154 offset:1024
	ds_read_b32 v129, v154 offset:1280
	ds_read_b32 v130, v154 offset:1536
	ds_read_b32 v131, v154 offset:1792
	v_lshlrev_b32_e32 v108, 16, v50
	v_and_b32_e32 v109, 0xffff0000, v50
	v_lshlrev_b32_e32 v110, 16, v58
	v_and_b32_e32 v111, 0xffff0000, v58
	v_lshlrev_b32_e32 v96, 16, v46
	v_and_b32_e32 v97, 0xffff0000, v46
	v_pk_add_f32 v[112:113], v[110:111], -1.0 op_sel_hi:[1,0]
	v_pk_mul_f32 v[114:115], v[12:13], v[108:109]
	v_pk_fma_f32 v[112:113], v[20:21], v[112:113], 1.0 op_sel_hi:[1,1,0]
	v_pk_mul_f32 v[88:89], v[62:63], v[114:115] op_sel_hi:[0,1]
	v_pk_mul_f32 v[72:73], v[112:113], v[108:109]
	v_pk_mul_f32 v[80:81], v[88:89], v[110:111]
	v_lshlrev_b32_e32 v108, 16, v51
	v_and_b32_e32 v109, 0xffff0000, v51
	v_lshlrev_b32_e32 v110, 16, v59
	v_and_b32_e32 v111, 0xffff0000, v59
	v_lshlrev_b32_e32 v98, 16, v47
	v_and_b32_e32 v99, 0xffff0000, v47
	v_pk_add_f32 v[112:113], v[110:111], -1.0 op_sel_hi:[1,0]
	v_pk_mul_f32 v[114:115], v[14:15], v[108:109]
	v_pk_fma_f32 v[112:113], v[22:23], v[112:113], 1.0 op_sel_hi:[1,1,0]
	v_pk_mul_f32 v[90:91], v[62:63], v[114:115] op_sel_hi:[0,1]
	v_pk_mul_f32 v[74:75], v[112:113], v[108:109]
	v_pk_mul_f32 v[82:83], v[90:91], v[110:111]
	v_lshlrev_b32_e32 v108, 16, v52
	v_and_b32_e32 v109, 0xffff0000, v52
	v_lshlrev_b32_e32 v110, 16, v60
	v_and_b32_e32 v111, 0xffff0000, v60
	v_lshlrev_b32_e32 v100, 16, v48
	v_and_b32_e32 v101, 0xffff0000, v48
	v_pk_add_f32 v[112:113], v[110:111], -1.0 op_sel_hi:[1,0]
	v_pk_mul_f32 v[114:115], v[16:17], v[108:109]
	v_pk_fma_f32 v[112:113], v[24:25], v[112:113], 1.0 op_sel_hi:[1,1,0]
	v_pk_mul_f32 v[92:93], v[62:63], v[114:115] op_sel_hi:[0,1]
	v_pk_mul_f32 v[76:77], v[112:113], v[108:109]
	v_pk_mul_f32 v[84:85], v[92:93], v[110:111]
	v_lshlrev_b32_e32 v108, 16, v53
	v_and_b32_e32 v109, 0xffff0000, v53
	v_lshlrev_b32_e32 v110, 16, v61
	v_and_b32_e32 v111, 0xffff0000, v61
	v_lshlrev_b32_e32 v102, 16, v49
	v_and_b32_e32 v103, 0xffff0000, v49
	v_pk_add_f32 v[112:113], v[110:111], -1.0 op_sel_hi:[1,0]
	v_pk_mul_f32 v[114:115], v[18:19], v[108:109]
	v_pk_fma_f32 v[112:113], v[26:27], v[112:113], 1.0 op_sel_hi:[1,1,0]
	v_pk_mul_f32 v[94:95], v[62:63], v[114:115] op_sel_hi:[0,1]
	v_pk_mul_f32 v[78:79], v[112:113], v[108:109]
	v_pk_mul_f32 v[86:87], v[94:95], v[110:111]
	v_lshlrev_b32_e32 v104, 16, v63
	v_and_b32_e32 v105, 0xffff0000, v63
	s_waitcnt lgkmcnt(0)
	v_add_f32_e32 v125, v124, v125
	v_add_f32_e32 v126, v125, v126
	v_add_f32_e32 v127, v126, v127
	v_add_f32_e32 v128, v127, v128
	v_add_f32_e32 v129, v128, v129
	v_add_f32_e32 v130, v129, v130
	v_add_f32_e32 v131, v130, v131
	v_exp_f32_e64 v124, -v124
	v_exp_f32_e64 v125, -v125
	v_exp_f32_e64 v126, -v126
	v_exp_f32_e64 v127, -v127
	v_exp_f32_e64 v128, -v128
	v_exp_f32_e64 v129, -v129
	v_exp_f32_e64 v130, -v130
	v_exp_f32_e64 v131, -v131
	s_nop 0
	ds_write_b32 v155, v124 offset:256
	ds_write_b32 v155, v125 offset:512
	ds_write_b32 v155, v126 offset:768
	ds_write_b32 v155, v127 offset:1024
	ds_write_b32 v155, v128 offset:1280
	ds_write_b32 v155, v129 offset:1536
	ds_write_b32 v155, v130 offset:1792
	ds_write_b32 v155, v131 offset:2048
	ds_write_b32 v159, v131 offset:34816
	s_waitcnt lgkmcnt(0)
	ds_read_b128 v[64:67], v153 offset:2048
	ds_read_b128 v[68:71], v153 offset:2176
	ds_read_b128 v[116:119], v153 offset:2304
	ds_read_b128 v[120:123], v153 offset:2432
	s_waitcnt lgkmcnt(0)
	v_rcp_f32_e32 v124, v116
	v_rcp_f32_e32 v125, v117
	v_rcp_f32_e32 v126, v118
	v_rcp_f32_e32 v127, v119
	v_rcp_f32_e32 v128, v120
	v_rcp_f32_e32 v129, v121
	v_rcp_f32_e32 v130, v122
	v_rcp_f32_e32 v131, v123
	s_nop 1
	v_pk_mul_f32 v[72:73], v[72:73], v[124:125]
	v_pk_mul_f32 v[80:81], v[80:81], v[124:125]
	v_pk_mul_f32 v[88:89], v[88:89], v[64:65]
	v_pk_mul_f32 v[96:97], v[96:97], v[116:117]
	v_pk_mul_f32 v[74:75], v[74:75], v[126:127]
	v_pk_mul_f32 v[82:83], v[82:83], v[126:127]
	v_pk_mul_f32 v[90:91], v[90:91], v[66:67]
	v_pk_mul_f32 v[98:99], v[98:99], v[118:119]
	v_pk_mul_f32 v[76:77], v[76:77], v[128:129]
	v_pk_mul_f32 v[84:85], v[84:85], v[128:129]
	v_pk_mul_f32 v[92:93], v[92:93], v[68:69]
	v_pk_mul_f32 v[100:101], v[100:101], v[120:121]
	v_pk_mul_f32 v[78:79], v[78:79], v[130:131]
	v_pk_mul_f32 v[86:87], v[86:87], v[130:131]
	v_pk_mul_f32 v[94:95], v[94:95], v[70:71]
	v_pk_mul_f32 v[102:103], v[102:103], v[122:123]
	ds_write_b128 v8, v[72:75] offset:34816
	ds_write_b128 v8, v[76:79] offset:34944
	ds_write_b128 v8, v[80:83] offset:35072
	ds_write_b128 v8, v[84:87] offset:35200
	ds_write2_b32 v140, v96, v97 offset0:1 offset1:3
	ds_write2_b32 v141, v88, v89 offset0:0 offset1:2
	ds_write2_b32 v140, v98, v99 offset0:65 offset1:67
	ds_write2_b32 v141, v90, v91 offset0:64 offset1:66
	ds_write2_b32 v140, v100, v101 offset0:33 offset1:35
	ds_write2_b32 v141, v92, v93 offset0:32 offset1:34
	ds_write2_b32 v140, v102, v103 offset0:97 offset1:99
	ds_write2_b32 v141, v94, v95 offset0:96 offset1:98
	ds_write2_b32 v143, v104, v105 offset1:36
	s_and_saveexec_b64 s[68:69], s[12:13]
	ds_write_b128 v158, v[88:91] offset:34816
	ds_write_b128 v158, v[92:95] offset:34944
	s_mov_b64 exec, s[68:69]
	global_load_dwordx2 v[46:47], v5, s[36:37]
	global_load_dwordx2 v[48:49], v5, s[36:37] offset:64
	global_load_dwordx2 v[50:51], v5, s[38:39]
	global_load_dwordx2 v[52:53], v5, s[38:39] offset:64
	global_load_dwordx2 v[54:55], v5, s[40:41]
	global_load_dwordx2 v[56:57], v5, s[40:41] offset:64
	global_load_dwordx2 v[58:59], v5, s[42:43]
	global_load_dwordx2 v[60:61], v5, s[42:43] offset:64
	global_load_dword v62, v6, s[46:47]
	global_load_dword v63, v9, s[44:45]
	v_add_u32_e32 v5, s54, v5
	v_add_u32_e32 v6, s55, v6
	v_add_u32_e32 v9, s54, v9
	ds_read_b128 v[120:123], v11 offset:16384
	ds_read_b128 v[124:127], v11 offset:16400
	ds_read_b128 v[128:131], v11 offset:16416
	ds_read_b128 v[132:135], v11 offset:16432
	s_waitcnt lgkmcnt(0)
	v_pk_add_f32 v[120:121], v[120:121], v[122:123]
	v_pk_add_f32 v[124:125], v[124:125], v[126:127]
	v_pk_add_f32 v[120:121], v[120:121], v[124:125]
	v_add_f32_e32 v136, v120, v121
	v_pk_add_f32 v[128:129], v[128:129], v[130:131]
	v_pk_add_f32 v[132:133], v[132:133], v[134:135]
	v_pk_add_f32 v[128:129], v[128:129], v[132:133]
	v_add_f32_e32 v137, v128, v129
	global_store_dwordx2 v7, v[136:137], s[48:49]
	v_add_u32_e32 v7, s64, v7
	s_add_i32 s6, s6, 1
	v_add_u32_e32 v146, 1, v146
	s_waitcnt lgkmcnt(0)
	ds_write_b32 v145, v146
	s_cmp_lt_u32 s6, 0xfe
	s_cbranch_scc1 .Lsc_G_loop
	s_sub_u32 s65, s6, 1
	s_mov_b32 s69, 0x100000

.Lsc_G_goz0:
	s_waitcnt vmcnt(10)
	v_lshlrev_b32_e32 v64, 16, v36
	v_and_b32_e32 v65, 0xffff0000, v36
	v_mul_f32_e32 v64, 0x3fb8aa3b, v64
	v_mul_f32_e32 v65, 0x3fb8aa3b, v65
	v_lshlrev_b32_e32 v66, 16, v37
	v_and_b32_e32 v67, 0xffff0000, v37
	v_mul_f32_e32 v66, 0x3fb8aa3b, v66
	v_mul_f32_e32 v67, 0x3fb8aa3b, v67
	v_lshlrev_b32_e32 v68, 16, v38
	v_and_b32_e32 v69, 0xffff0000, v38
	v_mul_f32_e32 v68, 0x3fb8aa3b, v68
	v_mul_f32_e32 v69, 0x3fb8aa3b, v69
	v_lshlrev_b32_e32 v70, 16, v39
	v_and_b32_e32 v71, 0xffff0000, v39
	v_mul_f32_e32 v70, 0x3fb8aa3b, v70
	v_mul_f32_e32 v71, 0x3fb8aa3b, v71
	ds_write_b128 v153, v[64:67]
	ds_write_b128 v153, v[68:71] offset:128
	s_waitcnt lgkmcnt(0)
	ds_read_b32 v124, v154 offset:0
	ds_read_b32 v125, v154 offset:256
	ds_read_b32 v126, v154 offset:512
	ds_read_b32 v127, v154 offset:768
	ds_read_b32 v128, v154 offset:1024
	ds_read_b32 v129, v154 offset:1280
	ds_read_b32 v130, v154 offset:1536
	ds_read_b32 v131, v154 offset:1792
	v_lshlrev_b32_e32 v108, 16, v32
	v_and_b32_e32 v109, 0xffff0000, v32
	v_lshlrev_b32_e32 v110, 16, v40
	v_and_b32_e32 v111, 0xffff0000, v40
	v_lshlrev_b32_e32 v96, 16, v28
	v_and_b32_e32 v97, 0xffff0000, v28
	v_pk_add_f32 v[112:113], v[110:111], -1.0 op_sel_hi:[1,0]
	v_pk_mul_f32 v[114:115], v[12:13], v[108:109]
	v_pk_fma_f32 v[112:113], v[20:21], v[112:113], 1.0 op_sel_hi:[1,1,0]
	v_pk_mul_f32 v[88:89], v[44:45], v[114:115] op_sel_hi:[0,1]
	v_pk_mul_f32 v[72:73], v[112:113], v[108:109]
	v_pk_mul_f32 v[80:81], v[88:89], v[110:111]
	v_lshlrev_b32_e32 v108, 16, v33
	v_and_b32_e32 v109, 0xffff0000, v33
	v_lshlrev_b32_e32 v110, 16, v41
	v_and_b32_e32 v111, 0xffff0000, v41
	v_lshlrev_b32_e32 v98, 16, v29
	v_and_b32_e32 v99, 0xffff0000, v29
	v_pk_add_f32 v[112:113], v[110:111], -1.0 op_sel_hi:[1,0]
	v_pk_mul_f32 v[114:115], v[14:15], v[108:109]
	v_pk_fma_f32 v[112:113], v[22:23], v[112:113], 1.0 op_sel_hi:[1,1,0]
	v_pk_mul_f32 v[90:91], v[44:45], v[114:115] op_sel_hi:[0,1]
	v_pk_mul_f32 v[74:75], v[112:113], v[108:109]
	v_pk_mul_f32 v[82:83], v[90:91], v[110:111]
	v_lshlrev_b32_e32 v108, 16, v34
	v_and_b32_e32 v109, 0xffff0000, v34
	v_lshlrev_b32_e32 v110, 16, v42
	v_and_b32_e32 v111, 0xffff0000, v42
	v_lshlrev_b32_e32 v100, 16, v30
	v_and_b32_e32 v101, 0xffff0000, v30
	v_pk_add_f32 v[112:113], v[110:111], -1.0 op_sel_hi:[1,0]
	v_pk_mul_f32 v[114:115], v[16:17], v[108:109]
	v_pk_fma_f32 v[112:113], v[24:25], v[112:113], 1.0 op_sel_hi:[1,1,0]
	v_pk_mul_f32 v[92:93], v[44:45], v[114:115] op_sel_hi:[0,1]
	v_pk_mul_f32 v[76:77], v[112:113], v[108:109]
	v_pk_mul_f32 v[84:85], v[92:93], v[110:111]
	v_lshlrev_b32_e32 v108, 16, v35
	v_and_b32_e32 v109, 0xffff0000, v35
	v_lshlrev_b32_e32 v110, 16, v43
	v_and_b32_e32 v111, 0xffff0000, v43
	v_lshlrev_b32_e32 v102, 16, v31
	v_and_b32_e32 v103, 0xffff0000, v31
	v_pk_add_f32 v[112:113], v[110:111], -1.0 op_sel_hi:[1,0]
	v_pk_mul_f32 v[114:115], v[18:19], v[108:109]
	v_pk_fma_f32 v[112:113], v[26:27], v[112:113], 1.0 op_sel_hi:[1,1,0]
	v_pk_mul_f32 v[94:95], v[44:45], v[114:115] op_sel_hi:[0,1]
	v_pk_mul_f32 v[78:79], v[112:113], v[108:109]
	v_pk_mul_f32 v[86:87], v[94:95], v[110:111]
	v_lshlrev_b32_e32 v104, 16, v45
	v_and_b32_e32 v105, 0xffff0000, v45
	s_waitcnt lgkmcnt(0)
	v_add_f32_e32 v125, v124, v125
	v_add_f32_e32 v126, v125, v126
	v_add_f32_e32 v127, v126, v127
	v_add_f32_e32 v128, v127, v128
	v_add_f32_e32 v129, v128, v129
	v_add_f32_e32 v130, v129, v130
	v_add_f32_e32 v131, v130, v131
	v_exp_f32_e64 v124, -v124
	v_exp_f32_e64 v125, -v125
	v_exp_f32_e64 v126, -v126
	v_exp_f32_e64 v127, -v127
	v_exp_f32_e64 v128, -v128
	v_exp_f32_e64 v129, -v129
	v_exp_f32_e64 v130, -v130
	v_exp_f32_e64 v131, -v131
	s_nop 0
	ds_write_b32 v155, v124 offset:256
	ds_write_b32 v155, v125 offset:512
	ds_write_b32 v155, v126 offset:768
	ds_write_b32 v155, v127 offset:1024
	ds_write_b32 v155, v128 offset:1280
	ds_write_b32 v155, v129 offset:1536
	ds_write_b32 v155, v130 offset:1792
	ds_write_b32 v155, v131 offset:2048
	ds_write_b32 v159, v131 offset:0
	s_waitcnt lgkmcnt(0)
	ds_read_b128 v[64:67], v153 offset:2048
	ds_read_b128 v[68:71], v153 offset:2176
	ds_read_b128 v[116:119], v153 offset:2304
	ds_read_b128 v[120:123], v153 offset:2432
	s_waitcnt lgkmcnt(0)
	v_rcp_f32_e32 v124, v116
	v_rcp_f32_e32 v125, v117
	v_rcp_f32_e32 v126, v118
	v_rcp_f32_e32 v127, v119
	v_rcp_f32_e32 v128, v120
	v_rcp_f32_e32 v129, v121
	v_rcp_f32_e32 v130, v122
	v_rcp_f32_e32 v131, v123
	s_nop 1
	v_pk_mul_f32 v[72:73], v[72:73], v[124:125]
	v_pk_mul_f32 v[80:81], v[80:81], v[124:125]
	v_pk_mul_f32 v[88:89], v[88:89], v[64:65]
	v_pk_mul_f32 v[96:97], v[96:97], v[116:117]
	v_pk_mul_f32 v[74:75], v[74:75], v[126:127]
	v_pk_mul_f32 v[82:83], v[82:83], v[126:127]
	v_pk_mul_f32 v[90:91], v[90:91], v[66:67]
	v_pk_mul_f32 v[98:99], v[98:99], v[118:119]
	v_pk_mul_f32 v[76:77], v[76:77], v[128:129]
	v_pk_mul_f32 v[84:85], v[84:85], v[128:129]
	v_pk_mul_f32 v[92:93], v[92:93], v[68:69]
	v_pk_mul_f32 v[100:101], v[100:101], v[120:121]
	v_pk_mul_f32 v[78:79], v[78:79], v[130:131]
	v_pk_mul_f32 v[86:87], v[86:87], v[130:131]
	v_pk_mul_f32 v[94:95], v[94:95], v[70:71]
	v_pk_mul_f32 v[102:103], v[102:103], v[122:123]
	ds_write_b128 v8, v[72:75] offset:0
	ds_write_b128 v8, v[76:79] offset:128
	ds_write_b128 v8, v[80:83] offset:256
	ds_write_b128 v8, v[84:87] offset:384
	ds_write2_b32 v138, v96, v97 offset0:1 offset1:3
	ds_write2_b32 v139, v88, v89 offset0:0 offset1:2
	ds_write2_b32 v138, v98, v99 offset0:65 offset1:67
	ds_write2_b32 v139, v90, v91 offset0:64 offset1:66
	ds_write2_b32 v138, v100, v101 offset0:33 offset1:35
	ds_write2_b32 v139, v92, v93 offset0:32 offset1:34
	ds_write2_b32 v138, v102, v103 offset0:97 offset1:99
	ds_write2_b32 v139, v94, v95 offset0:96 offset1:98
	ds_write2_b32 v142, v104, v105 offset1:36
	s_and_saveexec_b64 s[68:69], s[12:13]
	ds_write_b128 v158, v[88:91] offset:0
	ds_write_b128 v158, v[92:95] offset:128
	s_mov_b64 exec, s[68:69]
	ds_read_b128 v[120:123], v11 offset:0
	ds_read_b128 v[124:127], v11 offset:16
	ds_read_b128 v[128:131], v11 offset:32
	ds_read_b128 v[132:135], v11 offset:48
	s_waitcnt lgkmcnt(0)
	v_pk_add_f32 v[120:121], v[120:121], v[122:123]
	v_pk_add_f32 v[124:125], v[124:125], v[126:127]
	v_pk_add_f32 v[120:121], v[120:121], v[124:125]
	v_add_f32_e32 v136, v120, v121
	v_pk_add_f32 v[128:129], v[128:129], v[130:131]
	v_pk_add_f32 v[132:133], v[132:133], v[134:135]
	v_pk_add_f32 v[128:129], v[128:129], v[132:133]
	v_add_f32_e32 v137, v128, v129
	global_store_dwordx2 v7, v[136:137], s[48:49]
	v_add_u32_e32 v7, s64, v7
	s_add_i32 s6, s6, 1
	v_add_u32_e32 v146, 1, v146
	s_waitcnt lgkmcnt(0)
	ds_write_b32 v145, v146
	s_sub_u32 s65, s6, 1
	s_mov_b32 s69, 0x100000

.Lsc_G_goz1:
	s_waitcnt vmcnt(0)
	v_lshlrev_b32_e32 v64, 16, v54
	v_and_b32_e32 v65, 0xffff0000, v54
	v_mul_f32_e32 v64, 0x3fb8aa3b, v64
	v_mul_f32_e32 v65, 0x3fb8aa3b, v65
	v_lshlrev_b32_e32 v66, 16, v55
	v_and_b32_e32 v67, 0xffff0000, v55
	v_mul_f32_e32 v66, 0x3fb8aa3b, v66
	v_mul_f32_e32 v67, 0x3fb8aa3b, v67
	v_lshlrev_b32_e32 v68, 16, v56
	v_and_b32_e32 v69, 0xffff0000, v56
	v_mul_f32_e32 v68, 0x3fb8aa3b, v68
	v_mul_f32_e32 v69, 0x3fb8aa3b, v69
	v_lshlrev_b32_e32 v70, 16, v57
	v_and_b32_e32 v71, 0xffff0000, v57
	v_mul_f32_e32 v70, 0x3fb8aa3b, v70
	v_mul_f32_e32 v71, 0x3fb8aa3b, v71
	ds_write_b128 v153, v[64:67]
	ds_write_b128 v153, v[68:71] offset:128
	s_waitcnt lgkmcnt(0)
	ds_read_b32 v124, v154 offset:0
	ds_read_b32 v125, v154 offset:256
	ds_read_b32 v126, v154 offset:512
	ds_read_b32 v127, v154 offset:768
	ds_read_b32 v128, v154 offset:1024
	ds_read_b32 v129, v154 offset:1280
	ds_read_b32 v130, v154 offset:1536
	ds_read_b32 v131, v154 offset:1792
	v_lshlrev_b32_e32 v108, 16, v50
	v_and_b32_e32 v109, 0xffff0000, v50
	v_lshlrev_b32_e32 v110, 16, v58
	v_and_b32_e32 v111, 0xffff0000, v58
	v_lshlrev_b32_e32 v96, 16, v46
	v_and_b32_e32 v97, 0xffff0000, v46
	v_pk_add_f32 v[112:113], v[110:111], -1.0 op_sel_hi:[1,0]
	v_pk_mul_f32 v[114:115], v[12:13], v[108:109]
	v_pk_fma_f32 v[112:113], v[20:21], v[112:113], 1.0 op_sel_hi:[1,1,0]
	v_pk_mul_f32 v[88:89], v[62:63], v[114:115] op_sel_hi:[0,1]
	v_pk_mul_f32 v[72:73], v[112:113], v[108:109]
	v_pk_mul_f32 v[80:81], v[88:89], v[110:111]
	v_lshlrev_b32_e32 v108, 16, v51
	v_and_b32_e32 v109, 0xffff0000, v51
	v_lshlrev_b32_e32 v110, 16, v59
	v_and_b32_e32 v111, 0xffff0000, v59
	v_lshlrev_b32_e32 v98, 16, v47
	v_and_b32_e32 v99, 0xffff0000, v47
	v_pk_add_f32 v[112:113], v[110:111], -1.0 op_sel_hi:[1,0]
	v_pk_mul_f32 v[114:115], v[14:15], v[108:109]
	v_pk_fma_f32 v[112:113], v[22:23], v[112:113], 1.0 op_sel_hi:[1,1,0]
	v_pk_mul_f32 v[90:91], v[62:63], v[114:115] op_sel_hi:[0,1]
	v_pk_mul_f32 v[74:75], v[112:113], v[108:109]
	v_pk_mul_f32 v[82:83], v[90:91], v[110:111]
	v_lshlrev_b32_e32 v108, 16, v52
	v_and_b32_e32 v109, 0xffff0000, v52
	v_lshlrev_b32_e32 v110, 16, v60
	v_and_b32_e32 v111, 0xffff0000, v60
	v_lshlrev_b32_e32 v100, 16, v48
	v_and_b32_e32 v101, 0xffff0000, v48
	v_pk_add_f32 v[112:113], v[110:111], -1.0 op_sel_hi:[1,0]
	v_pk_mul_f32 v[114:115], v[16:17], v[108:109]
	v_pk_fma_f32 v[112:113], v[24:25], v[112:113], 1.0 op_sel_hi:[1,1,0]
	v_pk_mul_f32 v[92:93], v[62:63], v[114:115] op_sel_hi:[0,1]
	v_pk_mul_f32 v[76:77], v[112:113], v[108:109]
	v_pk_mul_f32 v[84:85], v[92:93], v[110:111]
	v_lshlrev_b32_e32 v108, 16, v53
	v_and_b32_e32 v109, 0xffff0000, v53
	v_lshlrev_b32_e32 v110, 16, v61
	v_and_b32_e32 v111, 0xffff0000, v61
	v_lshlrev_b32_e32 v102, 16, v49
	v_and_b32_e32 v103, 0xffff0000, v49
	v_pk_add_f32 v[112:113], v[110:111], -1.0 op_sel_hi:[1,0]
	v_pk_mul_f32 v[114:115], v[18:19], v[108:109]
	v_pk_fma_f32 v[112:113], v[26:27], v[112:113], 1.0 op_sel_hi:[1,1,0]
	v_pk_mul_f32 v[94:95], v[62:63], v[114:115] op_sel_hi:[0,1]
	v_pk_mul_f32 v[78:79], v[112:113], v[108:109]
	v_pk_mul_f32 v[86:87], v[94:95], v[110:111]
	v_lshlrev_b32_e32 v104, 16, v63
	v_and_b32_e32 v105, 0xffff0000, v63
	s_waitcnt lgkmcnt(0)
	v_add_f32_e32 v125, v124, v125
	v_add_f32_e32 v126, v125, v126
	v_add_f32_e32 v127, v126, v127
	v_add_f32_e32 v128, v127, v128
	v_add_f32_e32 v129, v128, v129
	v_add_f32_e32 v130, v129, v130
	v_add_f32_e32 v131, v130, v131
	v_exp_f32_e64 v124, -v124
	v_exp_f32_e64 v125, -v125
	v_exp_f32_e64 v126, -v126
	v_exp_f32_e64 v127, -v127
	v_exp_f32_e64 v128, -v128
	v_exp_f32_e64 v129, -v129
	v_exp_f32_e64 v130, -v130
	v_exp_f32_e64 v131, -v131
	s_nop 0
	ds_write_b32 v155, v124 offset:256
	ds_write_b32 v155, v125 offset:512
	ds_write_b32 v155, v126 offset:768
	ds_write_b32 v155, v127 offset:1024
	ds_write_b32 v155, v128 offset:1280
	ds_write_b32 v155, v129 offset:1536
	ds_write_b32 v155, v130 offset:1792
	ds_write_b32 v155, v131 offset:2048
	ds_write_b32 v159, v131 offset:34816
	s_waitcnt lgkmcnt(0)
	ds_read_b128 v[64:67], v153 offset:2048
	ds_read_b128 v[68:71], v153 offset:2176
	ds_read_b128 v[116:119], v153 offset:2304
	ds_read_b128 v[120:123], v153 offset:2432
	s_waitcnt lgkmcnt(0)
	v_rcp_f32_e32 v124, v116
	v_rcp_f32_e32 v125, v117
	v_rcp_f32_e32 v126, v118
	v_rcp_f32_e32 v127, v119
	v_rcp_f32_e32 v128, v120
	v_rcp_f32_e32 v129, v121
	v_rcp_f32_e32 v130, v122
	v_rcp_f32_e32 v131, v123
	s_nop 1
	v_pk_mul_f32 v[72:73], v[72:73], v[124:125]
	v_pk_mul_f32 v[80:81], v[80:81], v[124:125]
	v_pk_mul_f32 v[88:89], v[88:89], v[64:65]
	v_pk_mul_f32 v[96:97], v[96:97], v[116:117]
	v_pk_mul_f32 v[74:75], v[74:75], v[126:127]
	v_pk_mul_f32 v[82:83], v[82:83], v[126:127]
	v_pk_mul_f32 v[90:91], v[90:91], v[66:67]
	v_pk_mul_f32 v[98:99], v[98:99], v[118:119]
	v_pk_mul_f32 v[76:77], v[76:77], v[128:129]
	v_pk_mul_f32 v[84:85], v[84:85], v[128:129]
	v_pk_mul_f32 v[92:93], v[92:93], v[68:69]
	v_pk_mul_f32 v[100:101], v[100:101], v[120:121]
	v_pk_mul_f32 v[78:79], v[78:79], v[130:131]
	v_pk_mul_f32 v[86:87], v[86:87], v[130:131]
	v_pk_mul_f32 v[94:95], v[94:95], v[70:71]
	v_pk_mul_f32 v[102:103], v[102:103], v[122:123]
	ds_write_b128 v8, v[72:75] offset:34816
	ds_write_b128 v8, v[76:79] offset:34944
	ds_write_b128 v8, v[80:83] offset:35072
	ds_write_b128 v8, v[84:87] offset:35200
	ds_write2_b32 v140, v96, v97 offset0:1 offset1:3
	ds_write2_b32 v141, v88, v89 offset0:0 offset1:2
	ds_write2_b32 v140, v98, v99 offset0:65 offset1:67
	ds_write2_b32 v141, v90, v91 offset0:64 offset1:66
	ds_write2_b32 v140, v100, v101 offset0:33 offset1:35
	ds_write2_b32 v141, v92, v93 offset0:32 offset1:34
	ds_write2_b32 v140, v102, v103 offset0:97 offset1:99
	ds_write2_b32 v141, v94, v95 offset0:96 offset1:98
	ds_write2_b32 v143, v104, v105 offset1:36
	s_and_saveexec_b64 s[68:69], s[12:13]
	ds_write_b128 v158, v[88:91] offset:34816
	ds_write_b128 v158, v[92:95] offset:34944
	s_mov_b64 exec, s[68:69]
	ds_read_b128 v[120:123], v11 offset:16384
	ds_read_b128 v[124:127], v11 offset:16400
	ds_read_b128 v[128:131], v11 offset:16416
	ds_read_b128 v[132:135], v11 offset:16432
	s_waitcnt lgkmcnt(0)
	v_pk_add_f32 v[120:121], v[120:121], v[122:123]
	v_pk_add_f32 v[124:125], v[124:125], v[126:127]
	v_pk_add_f32 v[120:121], v[120:121], v[124:125]
	v_add_f32_e32 v136, v120, v121
	v_pk_add_f32 v[128:129], v[128:129], v[130:131]
	v_pk_add_f32 v[132:133], v[132:133], v[134:135]
	v_pk_add_f32 v[128:129], v[128:129], v[132:133]
	v_add_f32_e32 v137, v128, v129
	global_store_dwordx2 v7, v[136:137], s[48:49]
	v_add_u32_e32 v7, s64, v7
	s_add_i32 s6, s6, 1
	v_add_u32_e32 v146, 1, v146
	s_waitcnt lgkmcnt(0)
	ds_write_b32 v145, v146
	s_sub_u32 s65, s6, 1
	s_mov_b32 s69, 0x100000

.Lsc_G_goz2:
	ds_read_b128 v[120:123], v11 offset:0
	ds_read_b128 v[124:127], v11 offset:16
	ds_read_b128 v[128:131], v11 offset:32
	ds_read_b128 v[132:135], v11 offset:48
	s_waitcnt lgkmcnt(0)
	v_pk_add_f32 v[120:121], v[120:121], v[122:123]
	v_pk_add_f32 v[124:125], v[124:125], v[126:127]
	v_pk_add_f32 v[120:121], v[120:121], v[124:125]
	v_add_f32_e32 v136, v120, v121
	v_pk_add_f32 v[128:129], v[128:129], v[130:131]
	v_pk_add_f32 v[132:133], v[132:133], v[134:135]
	v_pk_add_f32 v[128:129], v[128:129], v[132:133]
	v_add_f32_e32 v137, v128, v129
	global_store_dwordx2 v7, v[136:137], s[48:49]
	v_add_u32_e32 v7, s64, v7
	s_add_i32 s6, s6, 1
	v_add_u32_e32 v146, 1, v146
	s_waitcnt lgkmcnt(0)
	ds_write_b32 v145, v146
	s_sub_u32 s65, s6, 1
	s_mov_b32 s69, 0x100000

.Lsc_G_goz3:
	ds_read_b128 v[120:123], v11 offset:16384
	ds_read_b128 v[124:127], v11 offset:16400
	ds_read_b128 v[128:131], v11 offset:16416
	ds_read_b128 v[132:135], v11 offset:16432
	s_waitcnt lgkmcnt(0)
	v_pk_add_f32 v[120:121], v[120:121], v[122:123]
	v_pk_add_f32 v[124:125], v[124:125], v[126:127]
	v_pk_add_f32 v[120:121], v[120:121], v[124:125]
	v_add_f32_e32 v136, v120, v121
	v_pk_add_f32 v[128:129], v[128:129], v[130:131]
	v_pk_add_f32 v[132:133], v[132:133], v[134:135]
	v_pk_add_f32 v[128:129], v[128:129], v[132:133]
	v_add_f32_e32 v137, v128, v129
	global_store_dwordx2 v7, v[136:137], s[48:49]
	v_add_u32_e32 v7, s64, v7
	s_add_i32 s6, s6, 1
	v_add_u32_e32 v146, 1, v146
	s_waitcnt lgkmcnt(0)
	ds_write_b32 v145, v146
